# phase-3 chunk-prep: unroll serialized global-load copy loops (8/6 loads issued back-to-back, counted vmcnt)
# speedup vs baseline: 1.0140x; 1.0140x over previous
.LBB0_525:
	s_or_b64 exec, exec, s[0:1]
	s_waitcnt vmcnt(9)
	v_and_b32_e32 v17, 15, v1
	s_movk_i32 s0, 0x400
	v_cmp_gt_i32_e32 vcc, s0, v1
	v_lshlrev_b32_e32 v0, 4, v17
	s_and_saveexec_b64 s[2:3], vcc
	v_readlane_b32 s40, v246, 41
	v_readlane_b32 s42, v246, 43
	v_readlane_b32 s43, v246, 44
	v_readlane_b32 s44, v246, 45
	v_readlane_b32 s45, v246, 46
	s_movk_i32 s11, 0x110
	s_movk_i32 s12, 0x2ff
	v_readlane_b32 s41, v246, 42
	v_readlane_b32 s46, v246, 47
	v_readlane_b32 s47, v246, 48
	v_readlane_b32 s48, v246, 49
	v_readlane_b32 s49, v246, 50
	v_readlane_b32 s50, v246, 51
	v_readlane_b32 s51, v246, 52
	v_readlane_b32 s52, v246, 53
	v_readlane_b32 s53, v246, 54
	v_readlane_b32 s54, v246, 55
	v_readlane_b32 s55, v246, 56
	s_cbranch_execz .LBB0_528
	s_lshr_b32 s4, s94, 1
	s_cmp_eq_u32 s10, 0
	s_cselect_b64 s[0:1], -1, 0
	s_lshl_b32 s4, s4, 6
	s_and_b32 s4, s4, 0x80
	v_lshl_or_b32 v2, v17, 3, s4
	s_mov_b64 s[4:5], 0
	s_waitcnt vmcnt(8)
	s_mov_b32 s38, 0x2000
	s_mov_b32 s39, 0
	s_cmp_eq_u32 s10, 0
	s_cbranch_scc1 .Lssd_ld_fwd
	s_mov_b32 s38, 0xffffe000
	s_mov_b32 s39, -1
.Lssd_ld_fwd:
	v_ashrrev_i32_e32 v5, 4, v1
	v_sub_u32_e32 v6, 63, v5
	v_cndmask_b32_e64 v6, v6, v5, s[0:1]
	v_add_u32_e32 v6, s9, v6
	v_ashrrev_i32_e32 v7, 31, v6
	v_lshlrev_b64 v[10:11], 9, v[6:7]
	v_lshl_or_b32 v10, v2, 1, v10
	v_lshl_add_u64 v[6:7], s[42:43], 0, v[10:11]
	v_lshl_add_u64 v[8:9], s[44:45], 0, v[10:11]
	global_load_dwordx4 v[204:207], v[6:7], off
	global_load_dwordx4 v[208:211], v[8:9], off
	v_lshl_add_u64 v[6:7], v[6:7], 0, s[38:39]
	v_lshl_add_u64 v[8:9], v[8:9], 0, s[38:39]
	global_load_dwordx4 v[212:215], v[6:7], off
	global_load_dwordx4 v[216:219], v[8:9], off
	v_lshl_add_u64 v[6:7], v[6:7], 0, s[38:39]
	v_lshl_add_u64 v[8:9], v[8:9], 0, s[38:39]
	global_load_dwordx4 v[220:223], v[6:7], off
	global_load_dwordx4 v[224:227], v[8:9], off
	v_lshl_add_u64 v[6:7], v[6:7], 0, s[38:39]
	v_lshl_add_u64 v[8:9], v[8:9], 0, s[38:39]
	global_load_dwordx4 v[228:231], v[6:7], off
	global_load_dwordx4 v[232:235], v[8:9], off
	v_mad_u64_u32 v[12:13], s[6:7], v5, s11, v[0:1]
	s_waitcnt vmcnt(7)
	ds_write_b128 v12, v[204:207]
	s_waitcnt vmcnt(6)
	ds_write_b128 v12, v[208:211] offset:17408
	s_waitcnt vmcnt(5)
	ds_write_b128 v12, v[212:215] offset:4352
	s_waitcnt vmcnt(4)
	ds_write_b128 v12, v[216:219] offset:21760
	s_waitcnt vmcnt(3)
	ds_write_b128 v12, v[220:223] offset:8704
	s_waitcnt vmcnt(2)
	ds_write_b128 v12, v[224:227] offset:26112
	s_waitcnt vmcnt(1)
	ds_write_b128 v12, v[228:231] offset:13056
	s_waitcnt vmcnt(0)
	ds_write_b128 v12, v[232:235] offset:30464

.LBB0_573:
	s_andn2_b64 vcc, exec, s[0:1]
	s_cbranch_vccnz .LBB0_341
	v_mov_b32_e32 v74, v139
	s_lshl_b32 s8, s66, 3
	s_movk_i32 s0, 0x200
	s_and_b32 s6, s66, 1
	s_bfe_u32 s7, s66, 0x20001
	s_andn2_b32 s8, s8, 63
	v_cmp_gt_i32_e32 vcc, s0, v74
	s_and_saveexec_b64 s[2:3], vcc
	s_movk_i32 s9, 0xff
	s_movk_i32 s12, 0x90
	s_cbranch_execz .LBB0_577
	s_cmp_eq_u32 s6, 0
	s_cselect_b64 s[0:1], -1, 0
	s_lshl_b32 s4, s7, 6
	v_and_b32_e32 v1, 7, v74
	v_lshl_or_b32 v0, v1, 3, s4
	v_lshlrev_b32_e32 v2, 4, v1
	s_mov_b64 s[4:5], 0
	s_mov_b32 s38, 0x4000
	s_mov_b32 s39, 0
	s_cmp_eq_u32 s6, 0
	s_cbranch_scc1 .Ldn_ld_fwd
	s_mov_b32 s38, 0xffffc000
	s_mov_b32 s39, -1
.Ldn_ld_fwd:
	v_ashrrev_i32_e32 v3, 3, v74
	v_sub_u32_e32 v4, 63, v3
	v_cndmask_b32_e64 v4, v4, v3, s[0:1]
	v_add_u32_e32 v4, s8, v4
	v_ashrrev_i32_e32 v5, 31, v4
	v_lshlrev_b64 v[8:9], 9, v[4:5]
	v_lshl_or_b32 v8, v0, 1, v8
	v_lshl_add_u64 v[4:5], s[78:79], 0, v[8:9]
	global_load_dwordx4 v[204:207], v[4:5], off
	v_lshl_add_u64 v[4:5], s[80:81], 0, v[8:9]
	global_load_dwordx4 v[208:211], v[4:5], off
	v_lshl_add_u64 v[4:5], s[82:83], 0, v[8:9]
	global_load_dwordx4 v[212:215], v[4:5], off
	v_lshl_add_u64 v[8:9], v[8:9], 0, s[38:39]
	v_lshl_add_u64 v[4:5], s[78:79], 0, v[8:9]
	global_load_dwordx4 v[216:219], v[4:5], off
	v_lshl_add_u64 v[4:5], s[80:81], 0, v[8:9]
	global_load_dwordx4 v[220:223], v[4:5], off
	v_lshl_add_u64 v[4:5], s[82:83], 0, v[8:9]
	global_load_dwordx4 v[224:227], v[4:5], off
	v_mad_u64_u32 v[10:11], s[10:11], v3, s12, v[2:3]
	s_waitcnt vmcnt(5)
	ds_write_b128 v10, v[204:207]
	s_waitcnt vmcnt(4)
	ds_write_b128 v10, v[208:211] offset:9216
	s_waitcnt vmcnt(3)
	ds_write_b128 v10, v[212:215] offset:18432
	s_waitcnt vmcnt(2)
	ds_write_b128 v10, v[216:219] offset:4608
	s_waitcnt vmcnt(1)
	ds_write_b128 v10, v[220:223] offset:13824
	s_waitcnt vmcnt(0)
	ds_write_b128 v10, v[224:227] offset:23040
